# MLA attention softmax: packed fma/add and max3 trees cut VALU count per tile
# speedup vs baseline: 1.0112x; 1.0081x over previous
;     ...
; #pragma unroll
;             for (int ni = 0; ni < 4; ++ni) mx = fmaxf(mx, fmaxf(fmaxf(s[mi][ni][0], s[mi][ni][1]), fmaxf(s[mi][ni][2], s[mi][ni][3])));
;             mx = fmaxf(mx, __shfl_xor(mx, 16)); mx = fmaxf(mx, __shfl_xor(mx, 32));
.LBB0_711:
	s_or_b64 exec, exec, s[0:1]
	v_max3_f32 v115, v76, v77, v78
	v_max3_f32 v132, v79, v72, v73
	v_max3_f32 v133, v74, v75, v84
	v_max3_f32 v151, v85, v86, v87
	v_max3_f32 v102, v92, v93, v94
	v_max3_f32 v115, v115, v132, v95
	v_max3_f32 v133, v133, v151, v102
	v_max3_f32 v115, v115, v133, s17
	v_mov_b32_e32 v132, v115
	s_nop 1
	v_permlane16_swap_b32_e32 v132, v115
	s_nop 0
	v_max_f32_e32 v115, v115, v132
	v_mov_b32_e32 v132, v115
	s_nop 1
	v_permlane32_swap_b32_e32 v132, v115
	s_nop 0
	v_max3_f32 v132, v100, v115, v132
	v_cmp_gt_f32_e32 vcc, v132, v100
	s_cbranch_vccz .LBB0_713
	v_sub_f32_e32 v100, v100, v132
	v_mul_f32_e32 v100, 0x3e16c740, v100
	v_exp_f32_e32 v100, v100
	s_nop 0
	v_mul_f32_e32 v120, v120, v100
	v_pk_mul_f32 v[22:23], v[22:23], v[100:101] op_sel_hi:[1,0]
	v_pk_mul_f32 v[20:21], v[20:21], v[100:101] op_sel_hi:[1,0]
	v_pk_mul_f32 v[14:15], v[14:15], v[100:101] op_sel_hi:[1,0]
	v_pk_mul_f32 v[12:13], v[12:13], v[100:101] op_sel_hi:[1,0]
	v_pk_mul_f32 v[6:7], v[6:7], v[100:101] op_sel_hi:[1,0]
	v_pk_mul_f32 v[4:5], v[4:5], v[100:101] op_sel_hi:[1,0]
	v_pk_mul_f32 v[18:19], v[18:19], v[100:101] op_sel_hi:[1,0]
	v_pk_mul_f32 v[16:17], v[16:17], v[100:101] op_sel_hi:[1,0]

; DEV unsigned pk_bf16(float lo, float hi) { const bf16x2_t v = __builtin_convertvector((f32x2){lo, hi}, bf16x2_t); return __builtin_bit_cast(unsigned, v); }
;     ...
; #pragma unroll
;             for (int ni = 0; ni < 4; ++ni) mx = fmaxf(mx, fmaxf(fmaxf(s[mi][ni][0], s[mi][ni][1]), fmaxf(s[mi][ni][2], s[mi][ni][3])));
;             mx = fmaxf(mx, __shfl_xor(mx, 16)); mx = fmaxf(mx, __shfl_xor(mx, 32));
;             const float mnew = fmaxf(mrun[mi], mx);
;             const float mc = mnew * scale_log2;
;             float ps = 0.f;
; #pragma unroll
;             for (int ni = 0; ni < 4; ++ni)
; #pragma unroll
;                 for (int r = 0; r < 4; ++r) { const float pv = __builtin_amdgcn_exp2f(__builtin_fmaf(s[mi][ni][r], scale_log2, -mc)); s[mi][ni][r] = pv; ps += pv; }
;             if (__builtin_amdgcn_ballot_w64(mnew > mrun[mi]) != 0ull) {
;                 const float alpha = __builtin_amdgcn_exp2f((mrun[mi] - mnew) * scale_log2);
;                 lrun[mi] *= alpha;
; #pragma unroll
;                 for (int di = 0; di < DV / 16; ++di) o[mi][di] *= alpha;
;             }
;             mrun[mi] = mnew;
;             lrun[mi] += ps;
; #pragma unroll
;             for (int s2 = 0; s2 < 2; ++s2) { const f32x4 a = s[mi][2 * s2], b = s[mi][2 * s2 + 1];
;                 const u32x4 pk = (u32x4){pk_bf16(a[0], a[1]), pk_bf16(a[2], a[3]), pk_bf16(b[0], b[1]), pk_bf16(b[2], b[3])};
;                 pf[mi][s2] = __builtin_bit_cast(bf16x8, pk); }
.LBB0_715:
	s_or_b64 exec, exec, s[0:1]
	v_mul_f32_e32 v100, 0xbe16c740, v132
	s_mov_b32 s0, 0x3e16c740
	v_pk_fma_f32 v[76:77], v[76:77], s[0:1], v[100:101] op_sel_hi:[1,0,0]
	v_pk_fma_f32 v[78:79], v[78:79], s[0:1], v[100:101] op_sel_hi:[1,0,0]
	v_pk_fma_f32 v[72:73], v[72:73], s[0:1], v[100:101] op_sel_hi:[1,0,0]
	v_pk_fma_f32 v[74:75], v[74:75], s[0:1], v[100:101] op_sel_hi:[1,0,0]
	v_pk_fma_f32 v[84:85], v[84:85], s[0:1], v[100:101] op_sel_hi:[1,0,0]
	v_pk_fma_f32 v[86:87], v[86:87], s[0:1], v[100:101] op_sel_hi:[1,0,0]
	v_pk_fma_f32 v[92:93], v[92:93], s[0:1], v[100:101] op_sel_hi:[1,0,0]
	v_pk_fma_f32 v[94:95], v[94:95], s[0:1], v[100:101] op_sel_hi:[1,0,0]
	v_exp_f32_e32 v76, v76
	v_exp_f32_e32 v77, v77
	v_exp_f32_e32 v78, v78
	v_exp_f32_e32 v79, v79
	v_exp_f32_e32 v72, v72
	v_exp_f32_e32 v73, v73
	v_exp_f32_e32 v74, v74
	v_exp_f32_e32 v75, v75
	v_exp_f32_e32 v84, v84
	v_exp_f32_e32 v85, v85
	v_exp_f32_e32 v86, v86
	v_exp_f32_e32 v87, v87
	v_exp_f32_e32 v92, v92
	v_exp_f32_e32 v93, v93
	v_exp_f32_e32 v94, v94
	v_exp_f32_e32 v95, v95
	v_pk_add_f32 v[104:105], v[76:77], v[78:79]
	v_pk_add_f32 v[106:107], v[72:73], v[74:75]
	v_pk_add_f32 v[108:109], v[84:85], v[86:87]
	v_pk_add_f32 v[110:111], v[92:93], v[94:95]
	v_pk_add_f32 v[104:105], v[104:105], v[106:107]
	v_pk_add_f32 v[108:109], v[108:109], v[110:111]
	v_pk_add_f32 v[104:105], v[104:105], v[108:109]
	s_nop 0
	v_add_f32_e32 v100, v104, v105
	v_add_f32_e32 v120, v100, v120
	v_max3_f32 v100, v52, v53, v54
	v_max3_f32 v104, v55, v40, v41
	v_max3_f32 v105, v42, v43, v56
	v_max3_f32 v106, v57, v58, v59
	v_max3_f32 v107, v68, v69, v70
	v_max3_f32 v100, v100, v104, v71
	v_max3_f32 v105, v105, v106, v107
	v_max3_f32 v100, v100, v105, s17
	v_mov_b32_e32 v103, v100
	s_nop 1
	v_permlane16_swap_b32_e32 v103, v100
	s_nop 0
	v_max_f32_e32 v100, v100, v103
	v_mov_b32_e32 v102, v100
	s_nop 1
	v_permlane32_swap_b32_e32 v102, v100
	s_nop 0
	v_max3_f32 v133, v101, v100, v102
	v_cmp_gt_f32_e32 vcc, v133, v101
	s_cbranch_vccz .LBB0_717
	v_sub_f32_e32 v100, v101, v133
	v_mul_f32_e32 v100, 0x3e16c740, v100
	v_exp_f32_e32 v100, v100
	s_nop 0
	v_mul_f32_e32 v121, v121, v100
	v_pk_mul_f32 v[30:31], v[30:31], v[100:101] op_sel_hi:[1,0]
	v_pk_mul_f32 v[28:29], v[28:29], v[100:101] op_sel_hi:[1,0]
	v_pk_mul_f32 v[10:11], v[10:11], v[100:101] op_sel_hi:[1,0]
	v_pk_mul_f32 v[8:9], v[8:9], v[100:101] op_sel_hi:[1,0]
	v_pk_mul_f32 v[2:3], v[2:3], v[100:101] op_sel_hi:[1,0]
	v_pk_mul_f32 v[0:1], v[0:1], v[100:101] op_sel_hi:[1,0]
	v_pk_mul_f32 v[26:27], v[26:27], v[100:101] op_sel_hi:[1,0]
	v_pk_mul_f32 v[24:25], v[24:25], v[100:101] op_sel_hi:[1,0]
.LBB0_717:
	v_mul_f32_e32 v100, 0xbe16c740, v133
	s_mov_b32 s0, 0x3e16c740
	v_lshl_add_u32 v151, s10, 1, v148
	v_add_u32_e32 v156, 0x3800, v151
	ds_read2_b64 v[152:155], v156 offset1:4
	v_pk_fma_f32 v[52:53], v[52:53], s[0:1], v[100:101] op_sel_hi:[1,0,0]
	v_pk_fma_f32 v[54:55], v[54:55], s[0:1], v[100:101] op_sel_hi:[1,0,0]
	v_pk_fma_f32 v[40:41], v[40:41], s[0:1], v[100:101] op_sel_hi:[1,0,0]
	v_pk_fma_f32 v[42:43], v[42:43], s[0:1], v[100:101] op_sel_hi:[1,0,0]
	v_pk_fma_f32 v[56:57], v[56:57], s[0:1], v[100:101] op_sel_hi:[1,0,0]
	v_pk_fma_f32 v[58:59], v[58:59], s[0:1], v[100:101] op_sel_hi:[1,0,0]
	v_pk_fma_f32 v[68:69], v[68:69], s[0:1], v[100:101] op_sel_hi:[1,0,0]
	v_pk_fma_f32 v[70:71], v[70:71], s[0:1], v[100:101] op_sel_hi:[1,0,0]
	v_exp_f32_e32 v52, v52
	v_exp_f32_e32 v53, v53
	v_exp_f32_e32 v54, v54
	v_exp_f32_e32 v55, v55
	v_exp_f32_e32 v40, v40
	v_exp_f32_e32 v41, v41
	v_exp_f32_e32 v42, v42
	v_exp_f32_e32 v43, v43
	v_exp_f32_e32 v56, v56
	v_exp_f32_e32 v57, v57
	v_exp_f32_e32 v58, v58
	v_exp_f32_e32 v59, v59
	v_exp_f32_e32 v68, v68
	v_exp_f32_e32 v69, v69
	v_exp_f32_e32 v70, v70
	v_exp_f32_e32 v71, v71
	v_cvt_pk_bf16_f32 v108, v76, v77
	v_cvt_pk_bf16_f32 v109, v78, v79
	v_cvt_pk_bf16_f32 v110, v72, v73
	v_cvt_pk_bf16_f32 v111, v74, v75
	v_cvt_pk_bf16_f32 v112, v52, v53
	v_cvt_pk_bf16_f32 v113, v54, v55
	v_cvt_pk_bf16_f32 v114, v40, v41
	v_cvt_pk_bf16_f32 v115, v42, v43
	v_pk_add_f32 v[104:105], v[52:53], v[54:55]
	v_pk_add_f32 v[106:107], v[40:41], v[42:43]
	v_pk_add_f32 v[102:103], v[56:57], v[58:59]
	v_pk_add_f32 v[100:101], v[68:69], v[70:71]
	v_pk_add_f32 v[104:105], v[104:105], v[106:107]
	v_pk_add_f32 v[100:101], v[100:101], v[102:103]
	v_pk_add_f32 v[104:105], v[104:105], v[100:101]
	s_nop 0
	v_add_f32_e32 v100, v104, v105
	v_add_f32_e32 v121, v100, v121
	s_waitcnt lgkmcnt(0)
	v_mfma_f32_16x16x32_bf16 v[20:23], v[152:155], v[108:111], v[20:23]
	v_mfma_f32_16x16x32_bf16 v[28:31], v[152:155], v[112:115], v[28:31]
	ds_read2_b64 v[152:155], v156 offset0:8 offset1:12
	v_cvt_pk_bf16_f32 v104, v84, v85
	v_cvt_pk_bf16_f32 v105, v86, v87
	v_cvt_pk_bf16_f32 v106, v92, v93
	v_cvt_pk_bf16_f32 v107, v94, v95
	v_cvt_pk_bf16_f32 v100, v56, v57
	v_cvt_pk_bf16_f32 v101, v58, v59
	v_cvt_pk_bf16_f32 v102, v68, v69
	v_cvt_pk_bf16_f32 v103, v70, v71
	v_add_u32_e32 v156, 0x4000, v151
	s_waitcnt lgkmcnt(0)
	v_mfma_f32_16x16x32_bf16 v[20:23], v[152:155], v[104:107], v[20:23]
	v_mfma_f32_16x16x32_bf16 v[28:31], v[152:155], v[100:103], v[28:31]
	ds_read2_b64 v[152:155], v156 offset0:32 offset1:36
	s_waitcnt lgkmcnt(0)
	v_mfma_f32_16x16x32_bf16 v[12:15], v[152:155], v[108:111], v[12:15]
	v_mfma_f32_16x16x32_bf16 v[8:11], v[152:155], v[112:115], v[8:11]
	ds_read2_b64 v[152:155], v156 offset0:40 offset1:44
	v_add_u32_e32 v156, 0x4800, v151
	v_add_u32_e32 v151, 0x5000, v151
	s_waitcnt lgkmcnt(0)
	v_mfma_f32_16x16x32_bf16 v[12:15], v[152:155], v[104:107], v[12:15]
	v_mfma_f32_16x16x32_bf16 v[8:11], v[152:155], v[100:103], v[8:11]
	ds_read2_b64 v[152:155], v156 offset0:64 offset1:68
	s_waitcnt lgkmcnt(0)
	v_mfma_f32_16x16x32_bf16 v[4:7], v[152:155], v[108:111], v[4:7]
	v_mfma_f32_16x16x32_bf16 v[0:3], v[152:155], v[112:115], v[0:3]
	ds_read2_b64 v[152:155], v156 offset0:72 offset1:76
	s_waitcnt lgkmcnt(0)
	v_mfma_f32_16x16x32_bf16 v[4:7], v[152:155], v[104:107], v[4:7]
	v_mfma_f32_16x16x32_bf16 v[0:3], v[152:155], v[100:103], v[0:3]
	ds_read2_b64 v[152:155], v151 offset0:96 offset1:100
	s_waitcnt lgkmcnt(0)
	v_mfma_f32_16x16x32_bf16 v[16:19], v[152:155], v[108:111], v[16:19]
	ds_read2_b64 v[108:111], v151 offset0:104 offset1:108
	v_mfma_f32_16x16x32_bf16 v[24:27], v[152:155], v[112:115], v[24:27]
	s_waitcnt lgkmcnt(0)
	v_mfma_f32_16x16x32_bf16 v[16:19], v[108:111], v[104:107], v[16:19]
	v_mfma_f32_16x16x32_bf16 v[24:27], v[108:111], v[100:103], v[24:27]
	v_mov_b64_e32 v[100:101], v[132:133]
